# P0 x/mem row conversion: four loads of a row issued together with counted waits
# speedup vs baseline: 1.0666x; 1.0023x over previous
; __device__ __forceinline__ u32x2 pk4(f32x4 v) { u32x2 r; r.x = pk2(v.x, v.y); r.y = pk2(v.z, v.w); return r; }
; __global__ void __launch_bounds__(NWAVES * 64, 2) mega(Args args) {
;     ...
;         for (int row = gw; row < MR + 2048; row += NGW) {
;             const float* src = row < MP ? args.in[0] + (size_t)row * DM : (row < MR ? args.in[1] + (size_t)(row - MP) * DM : args.in[6] + (size_t)(row - MR) * DM);
;             bf16_t* dstp = row < MR ? XB + (size_t)row * DM : MEMB + (size_t)(row - MR) * DM;
;             const f32x4* s4 = (const f32x4*)src + lane; u32x2* ob = (u32x2*)dstp + lane;
; #pragma unroll
;             for (int j = 0; j < 4; ++j) ob[64 * j] = pk4(s4[64 * j]);
;         }
.LBB0_108:
	s_lshl_b64 s[22:23], s[22:23], 12
	s_add_u32 s6, s6, s22
	s_addc_u32 s7, s7, s23
	v_lshl_add_u64 v[6:7], v[0:1], 4, s[6:7]
	global_load_dwordx4 v[2:5], v[6:7], off
	global_load_dwordx4 v[180:183], v[6:7], off offset:1024
	global_load_dwordx4 v[184:187], v[6:7], off offset:2048
	global_load_dwordx4 v[188:191], v[6:7], off offset:3072
	s_add_i32 s0, s4, 0xffffbf80
	s_ashr_i32 s5, s4, 31
	s_cmpk_lt_i32 s4, 0x4080
	v_readlane_b32 s22, v251, 58
	s_cselect_b32 s7, s5, 0
	s_cselect_b32 s6, s4, s0
	v_readlane_b32 s0, v251, 57
	v_readlane_b32 s23, v251, 59
	v_readlane_b32 s5, v251, 56
	s_cselect_b32 s0, s23, s0
	s_cselect_b32 s5, s22, s5
	s_lshl_b64 s[6:7], s[6:7], 11
	s_add_u32 s6, s5, s6
	s_addc_u32 s7, s0, s7
	v_lshl_add_u64 v[8:9], v[0:1], 3, s[6:7]
	s_add_i32 s6, s4, s90
	s_cmpk_gt_i32 s6, 0x487f
	s_waitcnt vmcnt(3)
	v_cvt_pk_bf16_f32 v2, v2, v3
	v_cvt_pk_bf16_f32 v3, v4, v5
	global_store_dwordx2 v[8:9], v[2:3], off
	s_waitcnt vmcnt(2)
	v_cvt_pk_bf16_f32 v180, v180, v181
	v_cvt_pk_bf16_f32 v181, v182, v183
	global_store_dwordx2 v[8:9], v[180:181], off offset:512
	s_waitcnt vmcnt(1)
	v_cvt_pk_bf16_f32 v184, v184, v185
	v_cvt_pk_bf16_f32 v185, v186, v187
	global_store_dwordx2 v[8:9], v[184:185], off offset:1024
	s_waitcnt vmcnt(0)
	v_cvt_pk_bf16_f32 v188, v188, v189
	v_cvt_pk_bf16_f32 v189, v190, v191
	global_store_dwordx2 v[8:9], v[188:189], off offset:1536
	s_cbranch_scc1 .LBB0_103

; __device__ __forceinline__ u32x2 pk4(f32x4 v) { u32x2 r; r.x = pk2(v.x, v.y); r.y = pk2(v.z, v.w); return r; }
; __global__ void __launch_bounds__(NWAVES * 64, 2) mega(Args args) {
;     ...
;         for (int row = gw; row < MR + 2048; row += NGW) {
;             const float* src = row < MP ? args.in[0] + (size_t)row * DM : (row < MR ? args.in[1] + (size_t)(row - MP) * DM : args.in[6] + (size_t)(row - MR) * DM);
;             bf16_t* dstp = row < MR ? XB + (size_t)row * DM : MEMB + (size_t)(row - MR) * DM;
;             const f32x4* s4 = (const f32x4*)src + lane; u32x2* ob = (u32x2*)dstp + lane;
; #pragma unroll
;             for (int j = 0; j < 4; ++j) ob[64 * j] = pk4(s4[64 * j]);
;         }
.LBB0_117:
	s_lshl_b64 s[22:23], s[22:23], 12
	s_add_u32 s4, s4, s22
	s_addc_u32 s5, s5, s23
	v_lshl_add_u64 v[6:7], v[0:1], 4, s[4:5]
	global_load_dwordx4 v[2:5], v[6:7], off
	global_load_dwordx4 v[180:183], v[6:7], off offset:1024
	global_load_dwordx4 v[184:187], v[6:7], off offset:2048
	global_load_dwordx4 v[188:191], v[6:7], off offset:3072
	s_add_i32 s0, s6, 0xffffbf80
	s_ashr_i32 s4, s6, 31
	s_cmpk_lt_i32 s6, 0x4080
	v_readlane_b32 s22, v251, 58
	s_cselect_b32 s5, s4, 0
	s_cselect_b32 s4, s6, s0
	v_readlane_b32 s0, v251, 57
	v_readlane_b32 s23, v251, 59
	v_readlane_b32 s7, v251, 56
	s_cselect_b32 s0, s23, s0
	s_cselect_b32 s7, s22, s7
	s_lshl_b64 s[4:5], s[4:5], 11
	s_add_u32 s4, s7, s4
	s_addc_u32 s5, s0, s5
	v_lshl_add_u64 v[8:9], v[0:1], 3, s[4:5]
	s_add_i32 s4, s6, s90
	s_cmpk_lt_i32 s4, 0x4000
	s_waitcnt vmcnt(3)
	v_cvt_pk_bf16_f32 v2, v2, v3
	v_cvt_pk_bf16_f32 v3, v4, v5
	global_store_dwordx2 v[8:9], v[2:3], off
	s_waitcnt vmcnt(2)
	v_cvt_pk_bf16_f32 v180, v180, v181
	v_cvt_pk_bf16_f32 v181, v182, v183
	global_store_dwordx2 v[8:9], v[180:181], off offset:512
	s_waitcnt vmcnt(1)
	v_cvt_pk_bf16_f32 v184, v184, v185
	v_cvt_pk_bf16_f32 v185, v186, v187
	global_store_dwordx2 v[8:9], v[184:185], off offset:1024
	s_waitcnt vmcnt(0)
	v_cvt_pk_bf16_f32 v188, v188, v189
	v_cvt_pk_bf16_f32 v189, v190, v191
	global_store_dwordx2 v[8:9], v[188:189], off offset:1536
	s_cbranch_scc1 .LBB0_120
	s_cmpk_lt_u32 s4, 0x4080
	s_cbranch_scc1 .LBB0_121
	s_add_i32 s0, s4, 0xffffbf80
	s_mov_b64 s[6:7], s[20:21]
	s_mov_b64 s[22:23], s[0:1]
	s_cbranch_execz .LBB0_122
	s_branch .LBB0_123
